# speedup vs baseline: 1.0449x; 1.0084x over previous
; DEV int otid() { int t = threadIdx.x; asm volatile("" : "+v"(t)); return t; }
; template <bool SWAP, class RowA, class Epi>
; DEV void gemm_tile(unsigned char* smem, RowA rowA, const bf16_t* Bt, int K, Epi epi) {
;   const int tid = otid(), lane = tid & 63, wid = tid >> 6, wr = wid >> 1, wc = wid & 1, fr = lane & 15, fq = lane >> 4;
;   const int r0 = tid >> 2;
;   const int a_w = (r0 >> 2) & 3, g_w = (((a_w ^ (a_w >> 1)) & 1) << 1) | (a_w >> 1);
;   const int cc = ((tid & 3) ^ g_w) * 8;
;   const int a_r = (fr >> 2) & 3, g_r = (((a_r ^ (a_r >> 1)) & 1) << 1) | (a_r >> 1);
;   const int rdoff = fr * 64 + ((fq ^ g_r) * 16);
;   const bf16_t* a0 = rowA(r0) + cc;
;   const bf16_t* a1 = rowA(r0 + 64) + cc;
;   const bf16_t* b0 = Bt + (size_t)r0 * K + cc;
;   const bf16_t* b1 = Bt + (size_t)(r0 + 64) * K + cc;
;   f32x4 acc[4][4];
; #pragma unroll
;   for (int m = 0; m < 4; ++m)
; #pragma unroll
;     for (int n = 0; n < 4; ++n) acc[m][n] = f32x4{0.f, 0.f, 0.f, 0.f};
;   const int nk = K / 32;
;   auto stage = [&](int kt, int buf) {
;     unsigned char* SA = smem + buf * 16384 + tid * 16;
;     unsigned char* SB = SA + 8192;
;     const int ko = kt * 32;
;     glds16(a0 + ko, SA); glds16(a1 + ko, SA + 4096);
;     glds16(b0 + ko, SB); glds16(b1 + ko, SB + 4096);
;   };
;   stage(0, 0);
; DEV void phase_moe2(const Params& p, int l, unsigned char* smem) {
;     ...
;   for (int t = blockIdx.x; t < ntile; t += gridDim.x) {
;     int e = 0;
;     while (s_tile[e + 1] <= t) ++e;
;     const int local = t - s_tile[e], cnt = s_cnt[e], nmt = (cnt + 127) >> 7;
;     const int mt = local / NTN_, nt = local % NTN_;
;     const int rowoff = s_off[e];
;     const float* bd = p.b_dn + (size_t)(l * 32 + e) * 1024;
;     const float* gl = p.glist + e * NTOK;
;     const bf16_t* A = p.act + (size_t)(rowoff + mt * 128) * 1024;
;     gemm_tile<true>(smem, [&](int r) { return A + (size_t)r * 1024; },
;       p.wdn_t + ((size_t)(l * 32 + e) * 1024 + nt * 128) * 1024, 1024,
.LBB0_717:
	v_mov_b32_e32 v0, s0
	ds_read_b32 v0, v0 offset:33032
	s_add_i32 s10, s10, 1
	s_add_i32 s0, s0, 4
	s_add_u32 s6, s6, 0x200000
	s_addc_u32 s7, s7, 0
	s_waitcnt lgkmcnt(0)
	v_cmp_ge_i32_e32 vcc, s18, v0
	s_cbranch_vccnz .LBB0_717
	v_mov_b32_e32 v0, s0
	ds_read_b32 v1, v0 offset:33024
	v_add_u32_e32 v0, 0x8000, v0
	v_mov_b32_e32 v12, v122
	ds_read2_b32 v[74:75], v0 offset1:32
	s_waitcnt lgkmcnt(1)
	v_readfirstlane_b32 s4, v1
	v_lshrrev_b32_e32 v5, 4, v12
	v_lshrrev_b32_e32 v6, 5, v12
	s_sub_i32 s4, s18, s4
	v_xor_b32_e32 v5, v5, v6
	s_ashr_i32 s5, s4, 31
	v_lshlrev_b32_e32 v5, 1, v5
	s_lshr_b32 s5, s5, 29
	v_bfe_u32 v7, v12, 5, 1
	v_and_b32_e32 v5, 2, v5
	v_and_b32_e32 v6, 3, v12
	s_add_i32 s5, s4, s5
	v_bitop3_b32 v13, v5, v6, v7 bitop3:0x36
	v_lshrrev_b32_e32 v5, 2, v12
	v_lshrrev_b32_e32 v6, 3, v12
	s_and_b32 s8, s5, 0x1fffff8
	s_lshl_b32 s5, s5, 4
	v_xor_b32_e32 v5, v5, v6
	s_sub_i32 s4, s4, s8
	s_and_b32 s8, s5, 0xffffff80
	v_lshlrev_b32_e32 v5, 1, v5
	s_waitcnt lgkmcnt(0)
	v_add_u32_e32 v0, s8, v75
	v_bfe_u32 v71, v12, 4, 2
	v_ashrrev_i32_e32 v4, 2, v12
	v_bfe_u32 v7, v12, 3, 1
	v_and_b32_e32 v5, 2, v5
	v_ashrrev_i32_e32 v1, 31, v0
	v_readlane_b32 s72, v166, 7
	s_lshl_b32 s4, s4, 7
	v_bitop3_b32 v14, v5, v71, v7 bitop3:0x36
	v_ashrrev_i32_e32 v5, 31, v4
	s_lshl_b64 s[0:1], s[10:11], 10
	v_lshlrev_b64 v[0:1], 11, v[0:1]
	v_readlane_b32 s80, v166, 15
	v_readlane_b32 s81, v166, 16
	s_ashr_i32 s5, s4, 31
	v_lshlrev_b64 v[4:5], 11, v[4:5]
	s_mov_b64 s[20:21], 0x20000
	v_lshl_add_u64 v[2:3], s[80:81], 0, v[0:1]
	s_add_u32 s16, s0, s4
	v_lshl_add_u64 v[6:7], v[4:5], 0, s[20:21]
	v_lshlrev_b32_e32 v78, 4, v12
	s_addc_u32 s17, s1, s5
	v_lshl_add_u64 v[8:9], v[2:3], 0, v[6:7]
	v_lshl_add_u64 v[2:3], v[2:3], 0, v[4:5]
	v_lshlrev_b32_e32 v68, 4, v13
	v_readfirstlane_b32 s9, v78
	s_lshl_b64 s[16:17], s[16:17], 11
	v_lshl_add_u64 v[2:3], v[2:3], 0, v[68:69]
	s_mov_b32 m0, s9
	s_add_u32 s16, s38, s16
	v_add_u32_e32 v2, 0x1000, v78
	s_addc_u32 s17, s39, s17
	v_add_u32_e32 v13, 0x2000, v78
	v_readfirstlane_b32 s9, v2
	v_lshl_add_u64 v[10:11], s[16:17], 0, v[4:5]
	v_lshl_add_u64 v[8:9], v[8:9], 0, v[68:69]
	s_mov_b32 m0, s9
	v_readfirstlane_b32 s9, v13
	v_add_u32_e32 v2, 0x3000, v78
	v_lshl_add_u64 v[6:7], s[16:17], 0, v[6:7]
	v_lshl_add_u64 v[10:11], v[10:11], 0, v[68:69]
	s_mov_b32 m0, s9
	v_readfirstlane_b32 s9, v2
	v_lshl_add_u64 v[6:7], v[6:7], 0, v[68:69]
	s_mov_b32 m0, s9
	v_lshl_add_u64 v[0:1], v[4:5], 0, v[0:1]
	v_or_b32_e32 v0, v0, v68
	s_lshl_b64 s[16:17], s[4:5], 11
	v_lshl_add_u64 v[64:65], s[80:81], 0, v[0:1]
	v_lshl_add_u64 v[0:1], v[4:5], 0, s[16:17]
	v_and_b32_e32 v73, 15, v12
	v_or_b32_e32 v0, v0, v68
	v_bfe_u32 v70, v12, 6, 1
	v_ashrrev_i32_e32 v72, 7, v12
	v_lshlrev_b32_e32 v2, 6, v73
	v_lshl_add_u64 v[66:67], s[6:7], 0, v[0:1]
	v_mov_b32_e32 v0, 0
	v_lshl_or_b32 v76, v14, 4, v2
	v_lshlrev_b32_e32 v77, 12, v72
	v_lshlrev_b32_e32 v79, 12, v70
	s_mov_b32 s5, 0
	s_mov_b64 s[6:7], 0
	v_mov_b32_e32 v1, v0
	v_mov_b32_e32 v2, v0
	v_mov_b32_e32 v3, v0
	s_waitcnt vmcnt(0)
	v_mov_b32_e32 v16, v0
	v_mov_b32_e32 v17, v0
	v_mov_b32_e32 v18, v0
	v_mov_b32_e32 v19, v0
	s_waitcnt vmcnt(0)
	v_mov_b32_e32 v32, v0
	v_mov_b32_e32 v33, v0
	v_mov_b32_e32 v34, v0
	v_mov_b32_e32 v35, v0
	v_mov_b32_e32 v40, v0
	v_mov_b32_e32 v41, v0
	v_mov_b32_e32 v42, v0
	v_mov_b32_e32 v43, v0
	v_mov_b32_e32 v4, v0
	v_mov_b32_e32 v5, v0
	v_mov_b32_e32 v6, v0
	v_mov_b32_e32 v7, v0
	v_mov_b32_e32 v20, v0
	v_mov_b32_e32 v21, v0
	v_mov_b32_e32 v22, v0
	v_mov_b32_e32 v23, v0
	v_mov_b32_e32 v36, v0
	v_mov_b32_e32 v37, v0
	v_mov_b32_e32 v38, v0
	v_mov_b32_e32 v39, v0
	v_mov_b32_e32 v44, v0
	v_mov_b32_e32 v45, v0
	v_mov_b32_e32 v46, v0
	v_mov_b32_e32 v47, v0
	v_mov_b32_e32 v8, v0
	v_mov_b32_e32 v9, v0
	v_mov_b32_e32 v10, v0
	v_mov_b32_e32 v11, v0
	v_mov_b32_e32 v24, v0
	v_mov_b32_e32 v25, v0
	v_mov_b32_e32 v26, v0
	v_mov_b32_e32 v27, v0
	v_mov_b32_e32 v48, v0
	v_mov_b32_e32 v49, v0
	v_mov_b32_e32 v50, v0
	v_mov_b32_e32 v51, v0
	v_mov_b32_e32 v52, v0
	v_mov_b32_e32 v53, v0
	v_mov_b32_e32 v54, v0
	v_mov_b32_e32 v55, v0
	v_mov_b32_e32 v12, v0
	v_mov_b32_e32 v13, v0
	v_mov_b32_e32 v14, v0
	v_mov_b32_e32 v15, v0
	v_mov_b32_e32 v28, v0
	v_mov_b32_e32 v29, v0
	v_mov_b32_e32 v30, v0
	v_mov_b32_e32 v31, v0
	v_mov_b32_e32 v56, v0
	v_mov_b32_e32 v57, v0
	v_mov_b32_e32 v58, v0
	v_mov_b32_e32 v59, v0
	v_mov_b32_e32 v60, v0
	v_mov_b32_e32 v61, v0
	v_mov_b32_e32 v62, v0
	v_mov_b32_e32 v63, v0
	v_readlane_b32 s73, v166, 8
	v_readlane_b32 s74, v166, 9
	v_readlane_b32 s75, v166, 10
	v_readlane_b32 s76, v166, 11
	v_readlane_b32 s77, v166, 12
	v_readlane_b32 s78, v166, 13
	v_readlane_b32 s79, v166, 14
	v_readlane_b32 s82, v166, 17
	v_readlane_b32 s83, v166, 18
	v_readlane_b32 s84, v166, 19
	v_readlane_b32 s85, v166, 20
	v_readlane_b32 s86, v166, 21
	v_readlane_b32 s87, v166, 22
	v_and_b32_e32 v90, 15, v122
	v_bfe_u32 v91, v122, 4, 2
	v_bfe_u32 v92, v122, 1, 3
	v_xor_b32_e32 v91, v91, v92
	v_lshlrev_b32_e32 v91, 4, v91
	v_lshl_or_b32 v76, v90, 7, v91
	v_lshlrev_b32_e32 v77, 1, v77
	v_lshlrev_b32_e32 v79, 1, v79
	v_and_b32_e32 v90, 7, v122
	v_bfe_u32 v91, v122, 4, 3
	v_xor_b32_e32 v90, v90, v91
	v_lshlrev_b32_e32 v90, 4, v90
	v_lshrrev_b32_e32 v91, 3, v122
	v_lshl_or_b32 v90, v91, 11, v90
	v_bfe_u32 v91, v122, 4, 2
	v_lshrrev_b32_e32 v92, 1, v91
	v_xor_b32_e32 v93, v91, v92
	v_and_b32_e32 v93, 1, v93
	v_lshl_or_b32 v92, v93, 1, v92
	v_and_b32_e32 v91, 3, v122
	v_xor_b32_e32 v91, v91, v92
	v_lshlrev_b32_e32 v91, 4, v91
	v_lshrrev_b32_e32 v92, 2, v122
	v_lshl_or_b32 v91, v92, 11, v91
	v_sub_u32_e32 v90, v90, v91
	v_ashrrev_i32_e32 v91, 31, v90
	v_lshl_add_u64 v[64:65], v[64:65], 0, v[90:91]
	v_lshl_add_u64 v[66:67], v[66:67], 0, v[90:91]
	s_mov_b32 s16, 0xffe00000
	s_mov_b32 s17, -1
	v_lshl_add_u64 v[66:67], v[66:67], 0, s[16:17]
; template <bool SWAP, class RowA, class Epi>
; DEV void gemm_tile(unsigned char* smem, RowA rowA, const bf16_t* Bt, int K, Epi epi) {
;     ...
;   for (int t = 0; t < nk; ++t) {
;     asm volatile("s_waitcnt vmcnt(0)" ::: "memory");
;     __syncthreads();
;     if (t + 1 < nk) stage(t + 1, (t + 1) & 1);
;     const unsigned char* SA = smem + (t & 1) * 16384;
;     const unsigned char* SB = SA + 8192;
;     bf16x8 At[4], Bl[4];
; #pragma unroll
;     for (int m = 0; m < 4; ++m) At[m] = *reinterpret_cast<const bf16x8*>(SA + (wr * 64 + m * 16) * 64 + rdoff);
; #pragma unroll
;     for (int n = 0; n < 4; ++n) Bl[n] = *reinterpret_cast<const bf16x8*>(SB + (wc * 64 + n * 16) * 64 + rdoff);
; #pragma unroll
;     for (int m = 0; m < 4; ++m)
; #pragma unroll
;       for (int n = 0; n < 4; ++n)
;         acc[m][n] = SWAP ? __builtin_amdgcn_mfma_f32_16x16x32_bf16(Bl[n], At[m], acc[m][n], 0, 0, 0)
;                          : __builtin_amdgcn_mfma_f32_16x16x32_bf16(At[m], Bl[n], acc[m][n], 0, 0, 0);
;   }
.LBB0_719:
	s_bitcmp1_b32 s6, 6
	s_cbranch_scc1 .Lpair_odd_719
	s_waitcnt lgkmcnt(0)
	s_barrier
	v_readfirstlane_b32 s16, v78
	s_mov_b32 m0, s16
	v_lshl_add_u64 v[90:91], v[64:65], 0, s[6:7]
	s_mov_b64 s[16:17], 0x10000
	global_load_lds_dwordx4 v[90:91], off
	s_add_i32 m0, m0, 0x1000
	v_lshl_add_u64 v[92:93], v[90:91], 0, s[16:17]
	global_load_lds_dwordx4 v[92:93], off
	s_add_i32 m0, m0, 0x1000
	v_lshl_add_u64 v[90:91], v[92:93], 0, s[16:17]
	global_load_lds_dwordx4 v[90:91], off
	s_add_i32 m0, m0, 0x1000
	v_lshl_add_u64 v[92:93], v[90:91], 0, s[16:17]
	global_load_lds_dwordx4 v[92:93], off
	s_add_i32 m0, m0, 0x1000
	v_lshl_add_u64 v[90:91], v[66:67], 0, s[6:7]
	global_load_lds_dwordx4 v[90:91], off
	s_add_i32 m0, m0, 0x1000
	v_lshl_add_u64 v[92:93], v[90:91], 0, s[16:17]
	global_load_lds_dwordx4 v[92:93], off
	s_add_i32 m0, m0, 0x1000
	v_lshl_add_u64 v[90:91], v[92:93], 0, s[16:17]
	global_load_lds_dwordx4 v[90:91], off
	s_add_i32 m0, m0, 0x1000
	v_lshl_add_u64 v[92:93], v[90:91], 0, s[16:17]
	global_load_lds_dwordx4 v[92:93], off
	s_waitcnt vmcnt(0)
	s_barrier
.Lpair_odd_719:
	s_and_b32 s5, s6, 64
	v_xor_b32_e32 v68, s5, v76
	v_add_u32_e32 v89, v68, v77
	v_add_u32_e32 v68, v68, v79
	ds_read_b128 v[90:93], v89
	ds_read_b128 v[94:97], v89 offset:2048
	ds_read_b128 v[98:101], v89 offset:4096
	ds_read_b128 v[102:105], v89 offset:6144
	ds_read_b128 v[106:109], v68 offset:16384
	ds_read_b128 v[110:113], v68 offset:18432
	ds_read_b128 v[114:117], v68 offset:20480
	ds_read_b128 v[118:121], v68 offset:22528
	s_waitcnt lgkmcnt(0)
	v_mfma_f32_16x16x32_bf16 v[60:63], v[106:109], v[90:93], v[60:63]
	s_add_u32 s6, s6, 64
	s_addc_u32 s7, s7, 0
	s_cmpk_eq_i32 s6, 0x7c0
	v_mfma_f32_16x16x32_bf16 v[56:59], v[110:113], v[90:93], v[56:59]
	v_mfma_f32_16x16x32_bf16 v[28:31], v[114:117], v[90:93], v[28:31]
	v_mfma_f32_16x16x32_bf16 v[12:15], v[118:121], v[90:93], v[12:15]
	v_mfma_f32_16x16x32_bf16 v[52:55], v[106:109], v[94:97], v[52:55]
	v_mfma_f32_16x16x32_bf16 v[48:51], v[110:113], v[94:97], v[48:51]
	v_mfma_f32_16x16x32_bf16 v[24:27], v[114:117], v[94:97], v[24:27]
	v_mfma_f32_16x16x32_bf16 v[8:11], v[118:121], v[94:97], v[8:11]
	v_mfma_f32_16x16x32_bf16 v[44:47], v[106:109], v[98:101], v[44:47]
	v_mfma_f32_16x16x32_bf16 v[36:39], v[110:113], v[98:101], v[36:39]
	v_mfma_f32_16x16x32_bf16 v[20:23], v[114:117], v[98:101], v[20:23]
	v_mfma_f32_16x16x32_bf16 v[4:7], v[118:121], v[98:101], v[4:7]
	v_mfma_f32_16x16x32_bf16 v[40:43], v[106:109], v[102:105], v[40:43]
	v_mfma_f32_16x16x32_bf16 v[32:35], v[110:113], v[102:105], v[32:35]
	v_mfma_f32_16x16x32_bf16 v[16:19], v[114:117], v[102:105], v[16:19]
	v_mfma_f32_16x16x32_bf16 v[0:3], v[118:121], v[102:105], v[0:3]
	s_cbranch_scc0 .LBB0_719
	v_xor_b32_e32 v89, 64, v76
	v_add_u32_e32 v68, v89, v79
	s_waitcnt vmcnt(0)
	s_waitcnt vmcnt(0)
	s_barrier
; DEV unsigned pack2(float a, float b) { return (unsigned)f2bf(a) | ((unsigned)f2bf(b) << 16); }
; template <bool SWAP, class RowA, class Epi>
; DEV void gemm_tile(unsigned char* smem, RowA rowA, const bf16_t* Bt, int K, Epi epi) {
;     ...
;   for (int t = 0; t < nk; ++t) {
;     asm volatile("s_waitcnt vmcnt(0)" ::: "memory");
;     __syncthreads();
;     if (t + 1 < nk) stage(t + 1, (t + 1) & 1);
;     const unsigned char* SA = smem + (t & 1) * 16384;
;     const unsigned char* SB = SA + 8192;
;     bf16x8 At[4], Bl[4];
; #pragma unroll
;     for (int m = 0; m < 4; ++m) At[m] = *reinterpret_cast<const bf16x8*>(SA + (wr * 64 + m * 16) * 64 + rdoff);
; #pragma unroll
;     for (int n = 0; n < 4; ++n) Bl[n] = *reinterpret_cast<const bf16x8*>(SB + (wc * 64 + n * 16) * 64 + rdoff);
; #pragma unroll
;     for (int m = 0; m < 4; ++m)
; #pragma unroll
;       for (int n = 0; n < 4; ++n)
;         acc[m][n] = SWAP ? __builtin_amdgcn_mfma_f32_16x16x32_bf16(Bl[n], At[m], acc[m][n], 0, 0, 0)
;                          : __builtin_amdgcn_mfma_f32_16x16x32_bf16(At[m], Bl[n], acc[m][n], 0, 0, 0);
;   }
; DEV void phase_moe2(const Params& p, int l, unsigned char* smem) {
;     ...
; #pragma unroll
;         for (int n = 0; n < 4; ++n) {
;           const int col = nt * 128 + wc * 64 + n * 16 + fq * 4;
;           const float4 b4 = *reinterpret_cast<const float4*>(bd + col);
; #pragma unroll
;           for (int m = 0; m < 4; ++m) {
;             const int i = mt * 128 + wr * 64 + m * 16 + fr;
;             if (i < cnt) {
;               const float g = gl[i];
;               *reinterpret_cast<uint2*>(p.out2 + (size_t)(rowoff + i) * 1024 + col) =
;                   make_uint2(pack2((acc[m][n][0] + b4.x) * g, (acc[m][n][1] + b4.y) * g), pack2((acc[m][n][2] + b4.z) * g, (acc[m][n][3] + b4.w) * g));
;             }
	ds_read_b128 v[90:93], v68 offset:16384
	v_add_u32_e32 v89, v89, v77
	ds_read_b128 v[94:97], v68 offset:18432
	ds_read_b128 v[76:79], v89
	ds_read_b128 v[98:101], v89 offset:2048
	ds_read_b128 v[102:105], v68 offset:20480
	ds_read_b128 v[106:109], v68 offset:22528
	s_waitcnt lgkmcnt(3)
	v_mfma_f32_16x16x32_bf16 v[64:67], v[90:93], v[76:79], v[60:63]
	v_readlane_b32 s72, v165, 7
	v_readlane_b32 s73, v165, 8
	s_lshl_b64 s[0:1], s[0:1], 2
	s_waitcnt lgkmcnt(2)
	v_mfma_f32_16x16x32_bf16 v[60:63], v[90:93], v[98:101], v[52:55]
	v_readlane_b32 s74, v165, 9
	v_readlane_b32 s75, v165, 10
	v_readlane_b32 s76, v165, 11
	v_mfma_f32_16x16x32_bf16 v[48:51], v[94:97], v[98:101], v[48:51]
	v_readlane_b32 s77, v165, 12
	s_mov_b64 s[60:61], s[72:73]
	s_add_u32 s0, s60, s0
	s_waitcnt lgkmcnt(1)
	v_mfma_f32_16x16x32_bf16 v[24:27], v[102:105], v[98:101], v[24:27]
	s_addc_u32 s1, s61, s1
	v_readlane_b32 s78, v165, 13
	v_readlane_b32 s79, v165, 14
	s_waitcnt lgkmcnt(0)
	v_mfma_f32_16x16x32_bf16 v[8:11], v[106:109], v[98:101], v[8:11]
	ds_read_b128 v[98:101], v89 offset:4096
	ds_read_b128 v[110:113], v89 offset:6144
	v_readlane_b32 s80, v165, 15
	v_readlane_b32 s81, v165, 16
	s_waitcnt lgkmcnt(1)
	v_mfma_f32_16x16x32_bf16 v[52:55], v[90:93], v[98:101], v[44:47]
	v_readlane_b32 s82, v165, 17
	v_readlane_b32 s83, v165, 18
	s_nop 0
	v_lshlrev_b32_e32 v44, 6, v70
	v_lshlrev_b32_e32 v45, 2, v71
	v_or3_b32 v70, v44, v45, s4
	v_ashrrev_i32_e32 v71, 31, v70
	v_mfma_f32_16x16x32_bf16 v[56:59], v[94:97], v[76:79], v[56:59]
	v_readlane_b32 s84, v165, 19
	v_readlane_b32 s85, v165, 20
	v_readlane_b32 s86, v165, 21
	v_mfma_f32_16x16x32_bf16 v[28:31], v[102:105], v[76:79], v[28:31]
	v_readlane_b32 s87, v165, 22
	s_mov_b64 s[62:63], s[74:75]
	s_mov_b64 s[64:65], s[76:77]
	v_mfma_f32_16x16x32_bf16 v[12:15], v[106:109], v[76:79], v[12:15]
	v_lshl_add_u64 v[76:77], v[70:71], 2, s[0:1]
	global_load_dwordx4 v[44:47], v[76:77], off
	s_mulk_i32 s10, 0x4200
	v_mfma_f32_16x16x32_bf16 v[36:39], v[94:97], v[98:101], v[36:39]
	v_readlane_b32 s72, v166, 7
	v_lshl_add_u32 v68, v72, 6, s8
	s_lshl_b64 s[0:1], s[10:11], 2
	v_mfma_f32_16x16x32_bf16 v[20:23], v[102:105], v[98:101], v[20:23]
	v_readlane_b32 s78, v166, 13
	v_or_b32_e32 v72, v68, v73
	v_readlane_b32 s79, v166, 14
	v_mfma_f32_16x16x32_bf16 v[4:7], v[106:109], v[98:101], v[4:7]
	s_add_u32 s0, s78, s0
	v_add_u32_e32 v78, v72, v75
	s_addc_u32 s1, s79, s1
	s_waitcnt lgkmcnt(0)
	v_mfma_f32_16x16x32_bf16 v[40:43], v[90:93], v[110:113], v[40:43]
	v_cmp_lt_i32_e32 vcc, v72, v74
	v_ashrrev_i32_e32 v73, 31, v72
	v_ashrrev_i32_e32 v79, 31, v78
	v_mfma_f32_16x16x32_bf16 v[32:35], v[94:97], v[110:113], v[32:35]
	v_readlane_b32 s73, v166, 8
	v_readlane_b32 s74, v166, 9
	v_readlane_b32 s75, v166, 10
	v_mfma_f32_16x16x32_bf16 v[16:19], v[102:105], v[110:113], v[16:19]
	v_readlane_b32 s76, v166, 11
	v_readlane_b32 s77, v166, 12
	v_readlane_b32 s80, v166, 15
	v_mfma_f32_16x16x32_bf16 v[0:3], v[106:109], v[110:113], v[0:3]
	v_readlane_b32 s81, v166, 16
	v_readlane_b32 s82, v166, 17
	v_readlane_b32 s83, v166, 18
	v_readlane_b32 s84, v166, 19
	v_readlane_b32 s85, v166, 20
	v_readlane_b32 s86, v166, 21
	v_readlane_b32 s87, v166, 22
	v_lshl_add_u64 v[124:125], v[72:73], 2, s[0:1]
	global_load_dword v126, v[124:125], off
	global_load_dword v127, v[124:125], off offset:64
	global_load_dword v128, v[124:125], off offset:128
	global_load_dword v129, v[124:125], off offset:192
	global_load_dwordx4 v[130:133], v[76:77], off offset:64
	global_load_dwordx4 v[134:137], v[76:77], off offset:128
	global_load_dwordx4 v[138:141], v[76:77], off offset:192
	s_waitcnt vmcnt(0)
	s_and_saveexec_b64 s[4:5], vcc
	s_cbranch_execz .LBB0_722
	v_lshl_add_u64 v[90:91], v[72:73], 2, s[0:1]
	v_mov_b32_e32 v68, v126
	v_pk_add_f32 v[66:67], v[66:67], v[46:47]
	v_pk_add_f32 v[64:65], v[64:65], v[44:45]
	v_mov_b32_e32 v93, v66
	v_mov_b32_e32 v66, v65
	v_mov_b32_e32 v92, v64
	v_readlane_b32 s72, v166, 7
	v_lshlrev_b64 v[90:91], 11, v[78:79]
	v_readlane_b32 s82, v166, 17
	v_readlane_b32 s83, v166, 18
	v_readlane_b32 s73, v166, 8
	v_readlane_b32 s74, v166, 9
	v_lshl_add_u64 v[90:91], s[82:83], 0, v[90:91]
	v_lshl_add_u64 v[90:91], v[70:71], 1, v[90:91]
	v_readlane_b32 s75, v166, 10
	v_readlane_b32 s76, v166, 11
	v_readlane_b32 s77, v166, 12
	v_readlane_b32 s78, v166, 13
	v_readlane_b32 s79, v166, 14
	v_readlane_b32 s80, v166, 15
	v_readlane_b32 s81, v166, 16
	v_readlane_b32 s84, v166, 19
	v_readlane_b32 s85, v166, 20
	v_readlane_b32 s86, v166, 21
	v_readlane_b32 s87, v166, 22
	v_pk_mul_f32 v[64:65], v[66:67], v[68:69] op_sel_hi:[1,0]
	v_pk_mul_f32 v[92:93], v[92:93], v[68:69] op_sel_hi:[1,0]
	v_and_b32_sdwa v68, v65, v87 dst_sel:DWORD dst_unused:UNUSED_PAD src0_sel:WORD_1 src1_sel:DWORD
	v_and_b32_sdwa v89, v64, v87 dst_sel:DWORD dst_unused:UNUSED_PAD src0_sel:WORD_1 src1_sel:DWORD
	v_and_b32_sdwa v66, v93, v87 dst_sel:DWORD dst_unused:UNUSED_PAD src0_sel:WORD_1 src1_sel:DWORD
	v_and_b32_sdwa v67, v92, v87 dst_sel:DWORD dst_unused:UNUSED_PAD src0_sel:WORD_1 src1_sel:DWORD
	v_add3_u32 v65, v65, v68, s2
	v_add3_u32 v64, v64, v89, s2
	v_add3_u32 v67, v92, v67, s2
	v_add3_u32 v66, v93, v66, s2
	v_and_b32_e32 v65, 0xffff0000, v65
	v_and_b32_e32 v64, 0xffff0000, v64
	v_or_b32_sdwa v65, v65, v66 dst_sel:DWORD dst_unused:UNUSED_PAD src0_sel:DWORD src1_sel:WORD_1
	v_or_b32_sdwa v64, v64, v67 dst_sel:DWORD dst_unused:UNUSED_PAD src0_sel:DWORD src1_sel:WORD_1
	global_store_dwordx2 v[90:91], v[64:65], off
